# sparse attention softmax: the token's reference (lazy running max, moved only when a block exceeds it by 2^8) rides into the QK MFMA as its C operand, so the per-score subtract, the per-block cross-la
# speedup vs baseline: 1.0253x; 1.0068x over previous
.LBB0_2063:
	s_or_b64 exec, exec, s[0:1]
	s_cmpk_gt_i32 s90, 0x3ff
	v_readlane_b32 s68, v251, 50
	v_readlane_b32 s69, v251, 51
	s_waitcnt lgkmcnt(0)
	s_barrier
	s_cbranch_scc1 .LBB0_2167
	v_readlane_b32 s0, v251, 7
	v_and_b32_e32 v112, 15, v152
	v_lshrrev_b32_e32 v113, 4, v152
	s_nop 1
	s_and_b32 s34, s0, 3
	s_lshr_b32 s35, s0, 2
	v_lshrrev_b32_e32 v220, 3, v153
	v_and_b32_e32 v221, 7, v153
	v_and_b32_e32 v222, 7, v220
	v_xor_b32_e32 v222, v222, v221
	v_lshlrev_b32_e32 v222, 4, v222
	v_lshl_add_u32 v114, v220, 7, v222
	v_mul_u32_u24_e32 v123, 0x90, v220
	v_lshl_add_u32 v123, v221, 4, v123
	v_add_u32_e32 v123, 0x2400, v123
	v_mul_u32_u24_e32 v117, 0x600, v220
	v_lshl_add_u32 v117, v221, 4, v117
	v_lshlrev_b32_e32 v118, 12, v220
	v_lshl_add_u32 v118, v221, 4, v118
	v_mul_u32_u24_e32 v116, 0x90, v112
	v_lshl_add_u32 v116, v113, 3, v116
	v_and_b32_e32 v222, 7, v112
	v_xor_b32_e32 v222, v222, v113
	v_lshlrev_b32_e32 v222, 4, v222
	v_lshl_add_u32 v115, v112, 7, v222
	v_xor_b32_e32 v122, 64, v115
	v_mov_b32_e32 v226, 0xf149f2ca
	v_mov_b32_e32 v227, 0xff61b1e6
	v_mov_b32_e32 v203, 0x41000000
	v_mov_b32_e32 v238, 0
	v_mov_b32_e32 v224, 0xff800000
	s_mov_b32 s26, s90
	s_mov_b32 s50, 0
.Lnsa_task:
	s_lshr_b32 s65, s26, 8
	s_and_b32 s1, s26, 255
	s_and_b32 s2, s1, 7
	s_lshr_b32 s1, s1, 3
	s_lshl_b32 s2, s2, 5
	s_or_b32 s1, s1, s2
	s_and_b32 s28, s1, 31
	s_sub_i32 s2, 31, s28
	s_bitcmp1_b32 s65, 0
	s_cselect_b32 s28, s2, s28
	s_lshr_b32 s29, s1, 5
	s_lshl_b32 s2, s65, 3
	s_add_i32 s29, s29, s2
	s_lshr_b32 s30, s29, 1
	s_and_b32 s31, s29, 1
	s_lshl_b32 s36, s31, 2
	s_add_i32 s36, s36, s34
	s_lshl_b32 s33, s28, 6
	s_mov_b32 s32, s28
	s_lshl_b32 s2, s35, 5
	s_add_i32 s2, s2, s33
	v_add_u32_e32 v86, s2, v112
	v_add_u32_e32 v87, 16, v86
	s_lshl_b32 s3, s30, 11
	v_add_u32_e32 v220, s3, v86
	v_lshlrev_b32_e32 v234, 10, v220
	s_lshl_b32 s4, s36, 7
	v_add_u32_e32 v234, s4, v234
	v_lshl_add_u32 v234, v113, 4, v234
	v_mov_b32_e32 v235, 0
	s_add_u32 s4, s96, 0xe000000
	s_addc_u32 s5, s97, 0
	v_lshl_add_u64 v[234:235], s[4:5], 0, v[234:235]
	global_load_dwordx4 v[160:163], v[234:235], off
	global_load_dwordx4 v[164:167], v[234:235], off offset:64
	v_lshlrev_b32_e32 v236, 8, v86
	v_lshl_add_u32 v236, v113, 6, v236
	s_add_u32 s4, s96, 0x2c00000
	s_addc_u32 s5, s97, 0
	global_load_dwordx4 v[124:127], v236, s[4:5] offset:0
	global_load_dwordx4 v[128:131], v236, s[4:5] offset:16
	global_load_dwordx4 v[132:135], v236, s[4:5] offset:32
	global_load_dwordx4 v[136:139], v236, s[4:5] offset:48
	s_lshl_b32 s6, s29, 11
	v_add_u32_e32 v221, s6, v86
	v_lshlrev_b32_e32 v221, 2, v221
	s_add_u32 s4, s96, 0x2e00000
	s_addc_u32 s5, s97, 0
	global_load_dword v84, v221, s[4:5]
	v_add_u32_e32 v220, s3, v87
	v_lshlrev_b32_e32 v234, 10, v220
	s_lshl_b32 s4, s36, 7
	v_add_u32_e32 v234, s4, v234
	v_lshl_add_u32 v234, v113, 4, v234
	v_mov_b32_e32 v235, 0
	s_add_u32 s4, s96, 0xe000000
	s_addc_u32 s5, s97, 0
	v_lshl_add_u64 v[234:235], s[4:5], 0, v[234:235]
	global_load_dwordx4 v[168:171], v[234:235], off
	global_load_dwordx4 v[172:175], v[234:235], off offset:64
	v_lshlrev_b32_e32 v236, 8, v87
	v_lshl_add_u32 v236, v113, 6, v236
	s_add_u32 s4, s96, 0x2c00000
	s_addc_u32 s5, s97, 0
	global_load_dwordx4 v[140:143], v236, s[4:5] offset:0
	global_load_dwordx4 v[144:147], v236, s[4:5] offset:16
	global_load_dwordx4 v[148:151], v236, s[4:5] offset:32
	global_load_dwordx4 v[154:157], v236, s[4:5] offset:48
	s_lshl_b32 s6, s29, 11
	v_add_u32_e32 v221, s6, v87
	v_lshlrev_b32_e32 v221, 2, v221
	s_add_u32 s4, s96, 0x2e00000
	s_addc_u32 s5, s97, 0
	global_load_dword v85, v221, s[4:5]
	s_lshl_b32 s3, s30, 11
	s_mul_i32 s2, s36, 6
	s_add_i32 s2, s2, 2
	s_add_u32 s8, s96, 0x13000000
	s_addc_u32 s9, s97, 0
	v_add_u32_e32 v223, s3, v86
	v_lshlrev_b32_e32 v223, 6, v223
	v_add_u32_e32 v223, s2, v223
	global_load_ushort v119, v223, s[8:9]
	global_load_ushort v158, v223, s[8:9] offset:2
	v_add_u32_e32 v223, s3, v87
	v_lshlrev_b32_e32 v223, 6, v223
	v_add_u32_e32 v223, s2, v223
	global_load_ushort v159, v223, s[8:9]
	global_load_ushort v233, v223, s[8:9] offset:2
	s_add_u32 s8, s96, 0x9000000
	s_addc_u32 s9, s97, 0
	v_add_u32_e32 v223, s3, v86
	v_lshlrev_b32_e32 v223, 10, v223
	s_lshl_b32 s2, s36, 7
	v_add_u32_e32 v223, s2, v223
	v_lshl_add_u32 v223, v113, 3, v223
	global_load_dwordx2 v[16:17], v223, s[8:9] offset:0
	global_load_dwordx2 v[20:21], v223, s[8:9] offset:32
	global_load_dwordx2 v[24:25], v223, s[8:9] offset:64
	global_load_dwordx2 v[28:29], v223, s[8:9] offset:96
	v_add_u32_e32 v223, s3, v87
	v_lshlrev_b32_e32 v223, 10, v223
	s_lshl_b32 s2, s36, 7
	v_add_u32_e32 v223, s2, v223
	v_lshl_add_u32 v223, v113, 3, v223
	global_load_dwordx2 v[32:33], v223, s[8:9] offset:0
	global_load_dwordx2 v[36:37], v223, s[8:9] offset:32
	global_load_dwordx2 v[40:41], v223, s[8:9] offset:64
	global_load_dwordx2 v[44:45], v223, s[8:9] offset:96
	s_mul_i32 s2, s30, 0x300000
	s_add_u32 s8, s96, 0x10000000
	s_addc_u32 s9, s97, 0
	s_add_u32 s8, s8, s2
	s_addc_u32 s9, s9, 0
	s_lshl_b32 s2, s31, 7
	s_add_u32 s8, s8, s2
	s_addc_u32 s9, s9, 0
	s_add_u32 s10, s8, 0x200
	s_addc_u32 s11, s9, 0
	global_load_dwordx4 v[88:91], v117, s[10:11]
	s_lshl_b32 s2, s29, 18
	s_add_u32 s10, s96, 0x1b200000
	s_addc_u32 s11, s97, 0
	s_add_u32 s10, s10, s2
	s_addc_u32 s11, s11, 0
	global_load_dwordx4 v[92:95], v118, s[10:11]
	s_add_i32 s12, s32, -8
	s_max_i32 s12, s12, 0
	s_mul_i32 s13, s12, 0x18000
	s_add_u32 s10, s8, 0x400
	s_addc_u32 s11, s9, 0
	s_add_u32 s10, s10, s13
	s_addc_u32 s11, s11, 0
	global_load_dwordx4 v[192:195], v117, s[10:11]
	s_lshl_b32 s13, s12, 7
	s_add_u32 s10, s96, 0x1ba00000
	s_addc_u32 s11, s97, 0
	s_add_u32 s10, s10, s2
	s_addc_u32 s11, s11, 0
	s_add_u32 s10, s10, s13
	s_addc_u32 s11, s11, 0
	global_load_dwordx4 v[196:199], v118, s[10:11]
	s_add_i32 s6, s6, s33
	v_add_u32_e32 v221, s6, v152
	v_lshlrev_b32_e32 v221, 2, v221
	global_load_dword v222, v221, s[4:5]
	s_waitcnt vmcnt(0)
	s_nop 1
	v_or_b32_dpp v222, v222, v222 quad_perm:[1,0,3,2] row_mask:0xf bank_mask:0xf bound_ctrl:1
	s_nop 1
	v_or_b32_dpp v222, v222, v222 quad_perm:[2,3,0,1] row_mask:0xf bank_mask:0xf bound_ctrl:1
	s_nop 1
	v_or_b32_dpp v222, v222, v222 row_ror:4 row_mask:0xf bank_mask:0xf bound_ctrl:1
	s_nop 1
	v_or_b32_dpp v222, v222, v222 row_ror:8 row_mask:0xf bank_mask:0xf bound_ctrl:1
	v_mov_b32_e32 v223, v222
	s_nop 1
	v_permlane16_swap_b32_e32 v222, v223
	v_or_b32_e32 v222, v222, v223
	v_mov_b32_e32 v223, v222
	s_nop 1
	v_permlane32_swap_b32_e32 v222, v223
	v_or_b32_e32 v222, v222, v223
	s_nop 0
	v_readfirstlane_b32 s39, v222
	s_mov_b32 s7, 0x3e38aa3b
	v_lshlrev_b32_e32 v220, 16, v160
	v_lshlrev_b32_e32 v221, 16, v164
	v_mul_f32_e32 v222, v221, v125
	v_fma_f32 v222, v220, v124, -v222
	v_mul_f32_e32 v223, v220, v125
	v_fma_f32 v223, v221, v124, v223
	v_mul_f32_e32 v240, s7, v222
	v_mul_f32_e32 v244, s7, v223
	v_and_b32_e32 v220, 0xffff0000, v160
	v_and_b32_e32 v221, 0xffff0000, v164
	v_mul_f32_e32 v222, v221, v127
	v_fma_f32 v222, v220, v126, -v222
	v_mul_f32_e32 v223, v220, v127
	v_fma_f32 v223, v221, v126, v223
	v_mul_f32_e32 v241, s7, v222
	v_mul_f32_e32 v245, s7, v223
	v_lshlrev_b32_e32 v220, 16, v161
	v_lshlrev_b32_e32 v221, 16, v165
	v_mul_f32_e32 v222, v221, v129
	v_fma_f32 v222, v220, v128, -v222
	v_mul_f32_e32 v223, v220, v129
	v_fma_f32 v223, v221, v128, v223
	v_mul_f32_e32 v242, s7, v222
	v_mul_f32_e32 v246, s7, v223
	v_and_b32_e32 v220, 0xffff0000, v161
	v_and_b32_e32 v221, 0xffff0000, v165
	v_mul_f32_e32 v222, v221, v131
	v_fma_f32 v222, v220, v130, -v222
	v_mul_f32_e32 v223, v220, v131
	v_fma_f32 v223, v221, v130, v223
	v_mul_f32_e32 v243, s7, v222
	v_mul_f32_e32 v247, s7, v223
	v_cvt_pk_bf16_f32 v0, v240, v241
	v_cvt_pk_bf16_f32 v1, v242, v243
	v_cvt_pk_bf16_f32 v4, v244, v245
	v_cvt_pk_bf16_f32 v5, v246, v247
	v_lshlrev_b32_e32 v220, 16, v162
	v_lshlrev_b32_e32 v221, 16, v166
	v_mul_f32_e32 v222, v221, v133
	v_fma_f32 v222, v220, v132, -v222
	v_mul_f32_e32 v223, v220, v133
	v_fma_f32 v223, v221, v132, v223
	v_mul_f32_e32 v240, s7, v222
	v_mul_f32_e32 v244, s7, v223
	v_and_b32_e32 v220, 0xffff0000, v162
	v_and_b32_e32 v221, 0xffff0000, v166
	v_mul_f32_e32 v222, v221, v135
	v_fma_f32 v222, v220, v134, -v222
	v_mul_f32_e32 v223, v220, v135
	v_fma_f32 v223, v221, v134, v223
	v_mul_f32_e32 v241, s7, v222
	v_mul_f32_e32 v245, s7, v223
	v_lshlrev_b32_e32 v220, 16, v163
	v_lshlrev_b32_e32 v221, 16, v167
	v_mul_f32_e32 v222, v221, v137
	v_fma_f32 v222, v220, v136, -v222
	v_mul_f32_e32 v223, v220, v137
	v_fma_f32 v223, v221, v136, v223
	v_mul_f32_e32 v242, s7, v222
	v_mul_f32_e32 v246, s7, v223
	v_and_b32_e32 v220, 0xffff0000, v163
	v_and_b32_e32 v221, 0xffff0000, v167
	v_mul_f32_e32 v222, v221, v139
	v_fma_f32 v222, v220, v138, -v222
	v_mul_f32_e32 v223, v220, v139
	v_fma_f32 v223, v221, v138, v223
	v_mul_f32_e32 v243, s7, v222
	v_mul_f32_e32 v247, s7, v223
	v_cvt_pk_bf16_f32 v2, v240, v241
	v_cvt_pk_bf16_f32 v3, v242, v243
	v_cvt_pk_bf16_f32 v6, v244, v245
	v_cvt_pk_bf16_f32 v7, v246, v247
	v_lshlrev_b32_e32 v220, 16, v168
	v_lshlrev_b32_e32 v221, 16, v172
	v_mul_f32_e32 v222, v221, v141
	v_fma_f32 v222, v220, v140, -v222
	v_mul_f32_e32 v223, v220, v141
	v_fma_f32 v223, v221, v140, v223
	v_mul_f32_e32 v240, s7, v222
	v_mul_f32_e32 v244, s7, v223
	v_and_b32_e32 v220, 0xffff0000, v168
	v_and_b32_e32 v221, 0xffff0000, v172
	v_mul_f32_e32 v222, v221, v143
	v_fma_f32 v222, v220, v142, -v222
	v_mul_f32_e32 v223, v220, v143
	v_fma_f32 v223, v221, v142, v223
	v_mul_f32_e32 v241, s7, v222
	v_mul_f32_e32 v245, s7, v223
	v_lshlrev_b32_e32 v220, 16, v169
	v_lshlrev_b32_e32 v221, 16, v173
	v_mul_f32_e32 v222, v221, v145
	v_fma_f32 v222, v220, v144, -v222
	v_mul_f32_e32 v223, v220, v145
	v_fma_f32 v223, v221, v144, v223
	v_mul_f32_e32 v242, s7, v222
	v_mul_f32_e32 v246, s7, v223
	v_and_b32_e32 v220, 0xffff0000, v169
	v_and_b32_e32 v221, 0xffff0000, v173
	v_mul_f32_e32 v222, v221, v147
	v_fma_f32 v222, v220, v146, -v222
	v_mul_f32_e32 v223, v220, v147
	v_fma_f32 v223, v221, v146, v223
	v_mul_f32_e32 v243, s7, v222
	v_mul_f32_e32 v247, s7, v223
	v_cvt_pk_bf16_f32 v8, v240, v241
	v_cvt_pk_bf16_f32 v9, v242, v243
	v_cvt_pk_bf16_f32 v12, v244, v245
	v_cvt_pk_bf16_f32 v13, v246, v247
	v_lshlrev_b32_e32 v220, 16, v170
	v_lshlrev_b32_e32 v221, 16, v174
	v_mul_f32_e32 v222, v221, v149
	v_fma_f32 v222, v220, v148, -v222
	v_mul_f32_e32 v223, v220, v149
	v_fma_f32 v223, v221, v148, v223
	v_mul_f32_e32 v240, s7, v222
	v_mul_f32_e32 v244, s7, v223
	v_and_b32_e32 v220, 0xffff0000, v170
	v_and_b32_e32 v221, 0xffff0000, v174
	v_mul_f32_e32 v222, v221, v151
	v_fma_f32 v222, v220, v150, -v222
	v_mul_f32_e32 v223, v220, v151
	v_fma_f32 v223, v221, v150, v223
	v_mul_f32_e32 v241, s7, v222
	v_mul_f32_e32 v245, s7, v223
	v_lshlrev_b32_e32 v220, 16, v171
	v_lshlrev_b32_e32 v221, 16, v175
	v_mul_f32_e32 v222, v221, v155
	v_fma_f32 v222, v220, v154, -v222
	v_mul_f32_e32 v223, v220, v155
	v_fma_f32 v223, v221, v154, v223
	v_mul_f32_e32 v242, s7, v222
	v_mul_f32_e32 v246, s7, v223
	v_and_b32_e32 v220, 0xffff0000, v171
	v_and_b32_e32 v221, 0xffff0000, v175
	v_mul_f32_e32 v222, v221, v157
	v_fma_f32 v222, v220, v156, -v222
	v_mul_f32_e32 v223, v220, v157
	v_fma_f32 v223, v221, v156, v223
	v_mul_f32_e32 v243, s7, v222
	v_mul_f32_e32 v247, s7, v223
	v_cvt_pk_bf16_f32 v10, v240, v241
	v_cvt_pk_bf16_f32 v11, v242, v243
	v_cvt_pk_bf16_f32 v14, v244, v245
	v_cvt_pk_bf16_f32 v15, v246, v247
	v_and_b32_e32 v19, 0xffff0000, v17
	v_lshlrev_b32_e32 v18, 16, v17
	v_and_b32_e32 v17, 0xffff0000, v16
	v_lshlrev_b32_e32 v16, 16, v16
	v_and_b32_e32 v23, 0xffff0000, v21
	v_lshlrev_b32_e32 v22, 16, v21
	v_and_b32_e32 v21, 0xffff0000, v20
	v_lshlrev_b32_e32 v20, 16, v20
	v_and_b32_e32 v27, 0xffff0000, v25
	v_lshlrev_b32_e32 v26, 16, v25
	v_and_b32_e32 v25, 0xffff0000, v24
	v_lshlrev_b32_e32 v24, 16, v24
	v_and_b32_e32 v31, 0xffff0000, v29
	v_lshlrev_b32_e32 v30, 16, v29
	v_and_b32_e32 v29, 0xffff0000, v28
	v_lshlrev_b32_e32 v28, 16, v28
	v_and_b32_e32 v35, 0xffff0000, v33
	v_lshlrev_b32_e32 v34, 16, v33
	v_and_b32_e32 v33, 0xffff0000, v32
	v_lshlrev_b32_e32 v32, 16, v32
	v_and_b32_e32 v39, 0xffff0000, v37
	v_lshlrev_b32_e32 v38, 16, v37
	v_and_b32_e32 v37, 0xffff0000, v36
	v_lshlrev_b32_e32 v36, 16, v36
	v_and_b32_e32 v43, 0xffff0000, v41
	v_lshlrev_b32_e32 v42, 16, v41
	v_and_b32_e32 v41, 0xffff0000, v40
	v_lshlrev_b32_e32 v40, 16, v40
	v_and_b32_e32 v47, 0xffff0000, v45
	v_lshlrev_b32_e32 v46, 16, v45
	v_and_b32_e32 v45, 0xffff0000, v44
	v_lshlrev_b32_e32 v44, 16, v44
	s_mov_b32 s37, 0

.Lnsa_brd_2:
	s_cmp_eq_u32 s37, 1
	s_mov_b32 s45, 0x7fffffff
	s_cselect_b32 s45, 0x200, s45
	s_add_i32 s14, s32, -8
	s_cmp_eq_u32 s37, 1
	s_cselect_b32 s14, s14, -2
	s_cselect_b64 vcc, -1, 0
	v_mov_b32_e32 v220, -1
	s_nop 1
	v_cndmask_b32_e32 v248, v84, v220, vcc
	v_cndmask_b32_e32 v249, v85, v220, vcc
	v_mov_b32_e32 v80, 0
	v_mov_b32_e32 v200, 0xefa18f08
	v_mov_b32_e32 v82, 0
	v_mov_b32_e32 v48, 0
	v_mov_b32_e32 v49, 0
	v_mov_b32_e32 v50, 0
	v_mov_b32_e32 v51, 0
	v_mov_b32_e32 v52, 0
	v_mov_b32_e32 v53, 0
	v_mov_b32_e32 v54, 0
	v_mov_b32_e32 v55, 0
	v_mov_b32_e32 v56, 0
	v_mov_b32_e32 v57, 0
	v_mov_b32_e32 v58, 0
	v_mov_b32_e32 v59, 0
	v_mov_b32_e32 v60, 0
	v_mov_b32_e32 v61, 0
	v_mov_b32_e32 v62, 0
	v_mov_b32_e32 v63, 0
	v_mov_b32_e32 v81, 0
	v_mov_b32_e32 v201, 0xefa18f08
	v_mov_b32_e32 v83, 0
	v_mov_b32_e32 v64, 0
	v_mov_b32_e32 v65, 0
	v_mov_b32_e32 v66, 0
	v_mov_b32_e32 v67, 0
	v_mov_b32_e32 v68, 0
	v_mov_b32_e32 v69, 0
	v_mov_b32_e32 v70, 0
	v_mov_b32_e32 v71, 0
	v_mov_b32_e32 v72, 0
	v_mov_b32_e32 v73, 0
	v_mov_b32_e32 v74, 0
	v_mov_b32_e32 v75, 0
	v_mov_b32_e32 v76, 0
	v_mov_b32_e32 v77, 0
	v_mov_b32_e32 v78, 0
	v_mov_b32_e32 v79, 0
	s_ff1_i32_b32 s15, s38
	s_add_i32 s65, s38, -1
	s_and_b32 s38, s38, s65
	s_ff1_i32_b32 s41, s38
	s_add_i32 s65, s38, -1
	s_and_b32 s38, s38, s65
	s_ff1_i32_b32 s42, s38
	s_add_i32 s65, s38, -1
	s_and_b32 s38, s38, s65
	s_cmp_eq_u32 s37, 1
	s_cbranch_scc0 .Lnsa_nopre_3
	v_mov_b32_e32 v88, v192
	v_mov_b32_e32 v92, v196
	v_mov_b32_e32 v89, v193
	v_mov_b32_e32 v93, v197
	v_mov_b32_e32 v90, v194
	v_mov_b32_e32 v94, v198
	v_mov_b32_e32 v91, v195
	v_mov_b32_e32 v95, v199
	s_branch .Lnsa_have0_4

.Lnsa_loop_5:
	s_cmp_lt_i32 s15, 0
	s_cbranch_scc1 .Lnsa_brk_6
	v_add_u32_e32 v225, s50, v115
	v_add_u32_e32 v246, s50, v122
	ds_read_b128 v[160:163], v225 offset:0
	ds_read_b128 v[168:171], v225 offset:2048
	ds_read_b128 v[176:179], v225 offset:4096
	ds_read_b128 v[184:187], v225 offset:6144
	ds_read_b128 v[164:167], v246 offset:0
	ds_read_b128 v[172:175], v246 offset:2048
	ds_read_b128 v[180:183], v246 offset:4096
	ds_read_b128 v[188:191], v246 offset:6144
	v_add_u32_e32 v247, s50, v116
	s_lshl_b32 s44, s15, 6
	s_lshl_b32 s65, 1, s15
	v_and_b32_e32 v220, s65, v248
	v_and_b32_e32 v221, s65, v249
	v_lshl_add_u32 v222, v113, 2, s44
	v_cmp_ne_u32_e64 s[60:61], 0, v220
	v_cmp_ne_u32_e64 s[62:63], 0, v221
	v_sub_u32_e32 v120, v86, v222
	v_sub_u32_e32 v121, v87, v222
	s_cmp_eq_u32 s15, s32
	s_cselect_b32 s64, 1, 0
	s_cmp_eq_u32 s15, s14
	s_cselect_b32 s64, 1, s64
	s_xor_b32 s17, s50, 0x4800
	v_add_u32_e32 v244, s17, v114
	v_add_u32_e32 v245, s17, v123
	v_cndmask_b32_e64 v228, v227, v80, s[60:61]
	v_cndmask_b32_e64 v229, v227, v80, s[60:61]
	v_cndmask_b32_e64 v230, v227, v80, s[60:61]
	v_cndmask_b32_e64 v231, v227, v80, s[60:61]
	v_cndmask_b32_e64 v236, v227, v81, s[62:63]
	v_cndmask_b32_e64 v237, v227, v81, s[62:63]
	v_cndmask_b32_e64 v238, v227, v81, s[62:63]
	v_cndmask_b32_e64 v239, v227, v81, s[62:63]
	s_waitcnt lgkmcnt(7)
	v_mfma_f32_16x16x32_bf16 v[124:127], v[160:163], v[0:3], v[228:231]
	s_waitcnt lgkmcnt(6)
	v_mfma_f32_16x16x32_bf16 v[128:131], v[168:171], v[0:3], v[228:231]
	s_waitcnt lgkmcnt(5)
	v_mfma_f32_16x16x32_bf16 v[132:135], v[176:179], v[0:3], v[228:231]
	s_waitcnt lgkmcnt(4)
	v_mfma_f32_16x16x32_bf16 v[136:139], v[184:187], v[0:3], v[228:231]
	s_waitcnt lgkmcnt(3)
	v_mfma_f32_16x16x32_bf16 v[124:127], v[164:167], v[4:7], v[124:127]
	s_waitcnt lgkmcnt(2)
	v_mfma_f32_16x16x32_bf16 v[128:131], v[172:175], v[4:7], v[128:131]
	s_waitcnt lgkmcnt(1)
	v_mfma_f32_16x16x32_bf16 v[132:135], v[180:183], v[4:7], v[132:135]
	s_waitcnt lgkmcnt(0)
	v_mfma_f32_16x16x32_bf16 v[136:139], v[188:191], v[4:7], v[136:139]
	s_waitcnt vmcnt(4)
	ds_write_b128 v244, v[96:99]
	ds_write_b128 v245, v[100:103]
	s_mov_b32 s16, s41
	s_ff1_i32_b32 s41, s38
	s_add_i32 s65, s38, -1
	s_and_b32 s38, s38, s65
	s_max_i32 s65, s41, 0
	s_mul_i32 s56, s65, 0x18000
	s_lshl_b32 s58, s65, 7
	s_add_u32 s56, s46, s56
	s_addc_u32 s57, s47, 0
	s_add_u32 s58, s48, s58
	s_addc_u32 s59, s49, 0
	global_load_dwordx4 v[96:99], v117, s[56:57]
	global_load_dwordx4 v[100:103], v118, s[58:59]
	s_cmp_eq_u32 s64, 0
	s_cbranch_scc1 .Lnsa_nm_7
	v_cndmask_b32_e64 v240, -1, v120, s[60:61]
	v_subrev_u32_e32 v220, 0, v240
	v_subrev_u32_e32 v221, 1, v240
	v_subrev_u32_e32 v222, 2, v240
	v_subrev_u32_e32 v223, 3, v240
	v_cmp_gt_u32_e64 s[52:53], s45, v220
	v_cmp_gt_u32_e64 s[54:55], s45, v221
	v_cmp_gt_u32_e64 s[56:57], s45, v222
	v_cmp_gt_u32_e64 s[58:59], s45, v223
	v_cndmask_b32_e64 v124, v224, v124, s[52:53]
	v_cndmask_b32_e64 v125, v224, v125, s[54:55]
	v_cndmask_b32_e64 v126, v224, v126, s[56:57]
	v_cndmask_b32_e64 v127, v224, v127, s[58:59]
	v_subrev_u32_e32 v220, 16, v240
	v_subrev_u32_e32 v221, 17, v240
	v_subrev_u32_e32 v222, 18, v240
	v_subrev_u32_e32 v223, 19, v240
	v_cmp_gt_u32_e64 s[52:53], s45, v220
	v_cmp_gt_u32_e64 s[54:55], s45, v221
	v_cmp_gt_u32_e64 s[56:57], s45, v222
	v_cmp_gt_u32_e64 s[58:59], s45, v223
	v_cndmask_b32_e64 v128, v224, v128, s[52:53]
	v_cndmask_b32_e64 v129, v224, v129, s[54:55]
	v_cndmask_b32_e64 v130, v224, v130, s[56:57]
	v_cndmask_b32_e64 v131, v224, v131, s[58:59]
	v_subrev_u32_e32 v220, 32, v240
	v_subrev_u32_e32 v221, 33, v240
	v_subrev_u32_e32 v222, 34, v240
	v_subrev_u32_e32 v223, 35, v240
	v_cmp_gt_u32_e64 s[52:53], s45, v220
	v_cmp_gt_u32_e64 s[54:55], s45, v221
	v_cmp_gt_u32_e64 s[56:57], s45, v222
	v_cmp_gt_u32_e64 s[58:59], s45, v223
	v_cndmask_b32_e64 v132, v224, v132, s[52:53]
	v_cndmask_b32_e64 v133, v224, v133, s[54:55]
	v_cndmask_b32_e64 v134, v224, v134, s[56:57]
	v_cndmask_b32_e64 v135, v224, v135, s[58:59]
	v_subrev_u32_e32 v220, 48, v240
	v_subrev_u32_e32 v221, 49, v240
	v_subrev_u32_e32 v222, 50, v240
	v_subrev_u32_e32 v223, 51, v240
	v_cmp_gt_u32_e64 s[52:53], s45, v220
	v_cmp_gt_u32_e64 s[54:55], s45, v221
	v_cmp_gt_u32_e64 s[56:57], s45, v222
	v_cmp_gt_u32_e64 s[58:59], s45, v223
	v_cndmask_b32_e64 v136, v224, v136, s[52:53]
	v_cndmask_b32_e64 v137, v224, v137, s[54:55]
	v_cndmask_b32_e64 v138, v224, v138, s[56:57]
	v_cndmask_b32_e64 v139, v224, v139, s[58:59]
.Lnsa_nm_7:
	v_mfma_f32_16x16x32_bf16 v[140:143], v[160:163], v[8:11], v[236:239]
	v_max3_f32 v220, v124, v125, v126
	v_max3_f32 v220, v220, v127, v128
	v_max3_f32 v220, v220, v129, v130
	v_mfma_f32_16x16x32_bf16 v[144:147], v[168:171], v[8:11], v[236:239]
	v_max3_f32 v220, v220, v131, v132
	v_max3_f32 v220, v220, v133, v134
	v_max3_f32 v220, v220, v135, v136
	v_mfma_f32_16x16x32_bf16 v[148:151], v[176:179], v[8:11], v[236:239]
	v_max3_f32 v220, v220, v137, v138
	v_max3_f32 v220, v220, v139, v226
	v_cmp_gt_f32_e32 vcc, v220, v200
	v_mfma_f32_16x16x32_bf16 v[154:157], v[184:187], v[8:11], v[236:239]
	s_cbranch_vccnz .Lnsa_rr_8
.Lnsa_rb_9:
	v_exp_f32_e32 v124, v124
	v_mfma_f32_16x16x32_bf16 v[140:143], v[164:167], v[12:15], v[140:143]
	v_exp_f32_e32 v125, v125
	v_exp_f32_e32 v126, v126
	v_exp_f32_e32 v127, v127
	v_mfma_f32_16x16x32_bf16 v[144:147], v[172:175], v[12:15], v[144:147]
	v_exp_f32_e32 v128, v128
	v_exp_f32_e32 v129, v129
	v_exp_f32_e32 v130, v130
	v_mfma_f32_16x16x32_bf16 v[148:151], v[180:183], v[12:15], v[148:151]
	v_exp_f32_e32 v131, v131
	v_exp_f32_e32 v132, v132
	v_exp_f32_e32 v133, v133
	v_mfma_f32_16x16x32_bf16 v[154:157], v[188:191], v[12:15], v[154:157]
	v_exp_f32_e32 v134, v134
	v_exp_f32_e32 v135, v135
	v_exp_f32_e32 v136, v136
	v_exp_f32_e32 v137, v137
	v_exp_f32_e32 v138, v138
	ds_read_b64 v[160:161], v247 offset:9216
	v_exp_f32_e32 v139, v139
	ds_read_b64 v[162:163], v247 offset:9248
	v_add_f32_e32 v232, v124, v125
	ds_read_b64 v[164:165], v247 offset:9280
	v_add_f32_e32 v232, v232, v126
	ds_read_b64 v[166:167], v247 offset:9312
	v_add_f32_e32 v232, v232, v127
	ds_read_b64 v[168:169], v247 offset:11520
	v_add_f32_e32 v232, v232, v128
	ds_read_b64 v[170:171], v247 offset:11552
	v_add_f32_e32 v232, v232, v129
	ds_read_b64 v[172:173], v247 offset:11584
	v_add_f32_e32 v232, v232, v130
	ds_read_b64 v[174:175], v247 offset:11616
	v_add_f32_e32 v232, v232, v131
	ds_read_b64 v[176:177], v247 offset:13824
	v_add_f32_e32 v232, v232, v132
	ds_read_b64 v[178:179], v247 offset:13856
	v_add_f32_e32 v232, v232, v133
	ds_read_b64 v[180:181], v247 offset:13888
	v_add_f32_e32 v232, v232, v134
	ds_read_b64 v[182:183], v247 offset:13920
	v_add_f32_e32 v232, v232, v135
	ds_read_b64 v[184:185], v247 offset:16128
	v_add_f32_e32 v232, v232, v136
	ds_read_b64 v[186:187], v247 offset:16160
	v_add_f32_e32 v232, v232, v137
	ds_read_b64 v[188:189], v247 offset:16192
	v_add_f32_e32 v232, v232, v138
	ds_read_b64 v[190:191], v247 offset:16224
	v_add_f32_e32 v232, v232, v139
	v_add_f32_e32 v82, v82, v232
	v_cvt_pk_bf16_f32 v204, v124, v125
	v_cvt_pk_bf16_f32 v205, v126, v127
	v_cvt_pk_bf16_f32 v206, v128, v129
	v_cvt_pk_bf16_f32 v207, v130, v131
	v_cvt_pk_bf16_f32 v208, v132, v133
	v_cvt_pk_bf16_f32 v209, v134, v135
	v_cvt_pk_bf16_f32 v210, v136, v137
	v_cvt_pk_bf16_f32 v211, v138, v139
	s_cmp_eq_u32 s64, 0
	s_cbranch_scc1 .Lnsa_nm_12
	v_cndmask_b32_e64 v240, -1, v121, s[62:63]
	v_subrev_u32_e32 v220, 0, v240
	v_subrev_u32_e32 v221, 1, v240
	v_subrev_u32_e32 v222, 2, v240
	v_subrev_u32_e32 v223, 3, v240
	v_cmp_gt_u32_e64 s[52:53], s45, v220
	v_cmp_gt_u32_e64 s[54:55], s45, v221
	v_cmp_gt_u32_e64 s[56:57], s45, v222
	v_cmp_gt_u32_e64 s[58:59], s45, v223
	v_cndmask_b32_e64 v140, v224, v140, s[52:53]
	v_cndmask_b32_e64 v141, v224, v141, s[54:55]
	v_cndmask_b32_e64 v142, v224, v142, s[56:57]
	v_cndmask_b32_e64 v143, v224, v143, s[58:59]
	v_subrev_u32_e32 v220, 16, v240
	v_subrev_u32_e32 v221, 17, v240
	v_subrev_u32_e32 v222, 18, v240
	v_subrev_u32_e32 v223, 19, v240
	v_cmp_gt_u32_e64 s[52:53], s45, v220
	v_cmp_gt_u32_e64 s[54:55], s45, v221
	v_cmp_gt_u32_e64 s[56:57], s45, v222
	v_cmp_gt_u32_e64 s[58:59], s45, v223
	v_cndmask_b32_e64 v144, v224, v144, s[52:53]
	v_cndmask_b32_e64 v145, v224, v145, s[54:55]
	v_cndmask_b32_e64 v146, v224, v146, s[56:57]
	v_cndmask_b32_e64 v147, v224, v147, s[58:59]
	v_subrev_u32_e32 v220, 32, v240
	v_subrev_u32_e32 v221, 33, v240
	v_subrev_u32_e32 v222, 34, v240
	v_subrev_u32_e32 v223, 35, v240
	v_cmp_gt_u32_e64 s[52:53], s45, v220
	v_cmp_gt_u32_e64 s[54:55], s45, v221
	v_cmp_gt_u32_e64 s[56:57], s45, v222
	v_cmp_gt_u32_e64 s[58:59], s45, v223
	v_cndmask_b32_e64 v148, v224, v148, s[52:53]
	v_cndmask_b32_e64 v149, v224, v149, s[54:55]
	v_cndmask_b32_e64 v150, v224, v150, s[56:57]
	v_cndmask_b32_e64 v151, v224, v151, s[58:59]
	v_subrev_u32_e32 v220, 48, v240
	v_subrev_u32_e32 v221, 49, v240
	v_subrev_u32_e32 v222, 50, v240
	v_subrev_u32_e32 v223, 51, v240
	v_cmp_gt_u32_e64 s[52:53], s45, v220
	v_cmp_gt_u32_e64 s[54:55], s45, v221
	v_cmp_gt_u32_e64 s[56:57], s45, v222
	v_cmp_gt_u32_e64 s[58:59], s45, v223
	v_cndmask_b32_e64 v154, v224, v154, s[52:53]
	v_cndmask_b32_e64 v155, v224, v155, s[54:55]
	v_cndmask_b32_e64 v156, v224, v156, s[56:57]
	v_cndmask_b32_e64 v157, v224, v157, s[58:59]
.Lnsa_nm_12:
	v_max3_f32 v220, v140, v141, v142
	v_max3_f32 v220, v220, v143, v144
	v_max3_f32 v220, v220, v145, v146
	v_max3_f32 v220, v220, v147, v148
	v_max3_f32 v220, v220, v149, v150
	v_max3_f32 v220, v220, v151, v154
	v_max3_f32 v220, v220, v155, v156
	v_max3_f32 v220, v220, v157, v226
	v_cmp_gt_f32_e32 vcc, v220, v201
	s_cbranch_vccnz .Lnsa_rr_10
.Lnsa_rb_11:
	s_waitcnt lgkmcnt(0)
	s_barrier
	s_mov_b32 s50, s17
	s_mov_b32 s15, s16
	v_mfma_f32_16x16x32_bf16 v[48:51], v[160:163], v[204:207], v[48:51]
	v_exp_f32_e32 v140, v140
	v_exp_f32_e32 v141, v141
	v_exp_f32_e32 v142, v142
	v_exp_f32_e32 v143, v143
	v_mfma_f32_16x16x32_bf16 v[52:55], v[168:171], v[204:207], v[52:55]
	v_exp_f32_e32 v144, v144
	v_exp_f32_e32 v145, v145
	v_exp_f32_e32 v146, v146
	v_exp_f32_e32 v147, v147
	v_mfma_f32_16x16x32_bf16 v[56:59], v[176:179], v[204:207], v[56:59]
	v_exp_f32_e32 v148, v148
	v_exp_f32_e32 v149, v149
	v_exp_f32_e32 v150, v150
	v_exp_f32_e32 v151, v151
	v_mfma_f32_16x16x32_bf16 v[60:63], v[184:187], v[204:207], v[60:63]
	v_exp_f32_e32 v154, v154
	v_exp_f32_e32 v155, v155
	v_exp_f32_e32 v156, v156
	v_exp_f32_e32 v157, v157
	v_mfma_f32_16x16x32_bf16 v[48:51], v[164:167], v[208:211], v[48:51]
	v_add_f32_e32 v232, v140, v141
	v_add_f32_e32 v232, v232, v142
	v_add_f32_e32 v232, v232, v143
	v_add_f32_e32 v232, v232, v144
	v_mfma_f32_16x16x32_bf16 v[52:55], v[172:175], v[208:211], v[52:55]
	v_add_f32_e32 v232, v232, v145
	v_add_f32_e32 v232, v232, v146
	v_add_f32_e32 v232, v232, v147
	v_add_f32_e32 v232, v232, v148
	v_mfma_f32_16x16x32_bf16 v[56:59], v[180:183], v[208:211], v[56:59]
	v_add_f32_e32 v232, v232, v149
	v_add_f32_e32 v232, v232, v150
	v_add_f32_e32 v232, v232, v151
	v_add_f32_e32 v232, v232, v154
	v_mfma_f32_16x16x32_bf16 v[60:63], v[188:191], v[208:211], v[60:63]
	v_add_f32_e32 v232, v232, v155
	v_add_f32_e32 v232, v232, v156
	v_add_f32_e32 v232, v232, v157
	v_add_f32_e32 v83, v83, v232
	v_cvt_pk_bf16_f32 v212, v140, v141
	v_cvt_pk_bf16_f32 v213, v142, v143
	v_cvt_pk_bf16_f32 v214, v144, v145
	v_cvt_pk_bf16_f32 v215, v146, v147
	v_cvt_pk_bf16_f32 v216, v148, v149
	v_cvt_pk_bf16_f32 v217, v150, v151
	v_cvt_pk_bf16_f32 v218, v154, v155
	v_cvt_pk_bf16_f32 v219, v156, v157
	v_mfma_f32_16x16x32_bf16 v[64:67], v[160:163], v[212:215], v[64:67]
	v_mfma_f32_16x16x32_bf16 v[68:71], v[168:171], v[212:215], v[68:71]
	v_mfma_f32_16x16x32_bf16 v[72:75], v[176:179], v[212:215], v[72:75]
	v_mfma_f32_16x16x32_bf16 v[76:79], v[184:187], v[212:215], v[76:79]
	v_mfma_f32_16x16x32_bf16 v[64:67], v[164:167], v[216:219], v[64:67]
	v_mfma_f32_16x16x32_bf16 v[68:71], v[172:175], v[216:219], v[68:71]
	v_mfma_f32_16x16x32_bf16 v[72:75], v[180:183], v[216:219], v[72:75]
	v_mfma_f32_16x16x32_bf16 v[76:79], v[188:191], v[216:219], v[76:79]
	s_cmp_lt_i32 s15, 0
	s_cbranch_scc1 .Lnsa_brk_6
	v_add_u32_e32 v225, s50, v115
	v_add_u32_e32 v246, s50, v122
	ds_read_b128 v[160:163], v225 offset:0
	ds_read_b128 v[168:171], v225 offset:2048
	ds_read_b128 v[176:179], v225 offset:4096
	ds_read_b128 v[184:187], v225 offset:6144
	ds_read_b128 v[164:167], v246 offset:0
	ds_read_b128 v[172:175], v246 offset:2048
	ds_read_b128 v[180:183], v246 offset:4096
	ds_read_b128 v[188:191], v246 offset:6144
	v_add_u32_e32 v247, s50, v116
	s_lshl_b32 s44, s15, 6
	s_lshl_b32 s65, 1, s15
	v_and_b32_e32 v220, s65, v248
	v_and_b32_e32 v221, s65, v249
	v_lshl_add_u32 v222, v113, 2, s44
	v_cmp_ne_u32_e64 s[60:61], 0, v220
	v_cmp_ne_u32_e64 s[62:63], 0, v221
	v_sub_u32_e32 v120, v86, v222
	v_sub_u32_e32 v121, v87, v222
	s_cmp_eq_u32 s15, s32
	s_cselect_b32 s64, 1, 0
	s_cmp_eq_u32 s15, s14
	s_cselect_b32 s64, 1, s64
	s_xor_b32 s17, s50, 0x4800
	v_add_u32_e32 v244, s17, v114
	v_add_u32_e32 v245, s17, v123
	v_cndmask_b32_e64 v228, v227, v80, s[60:61]
	v_cndmask_b32_e64 v229, v227, v80, s[60:61]
	v_cndmask_b32_e64 v230, v227, v80, s[60:61]
	v_cndmask_b32_e64 v231, v227, v80, s[60:61]
	v_cndmask_b32_e64 v236, v227, v81, s[62:63]
	v_cndmask_b32_e64 v237, v227, v81, s[62:63]
	v_cndmask_b32_e64 v238, v227, v81, s[62:63]
	v_cndmask_b32_e64 v239, v227, v81, s[62:63]
	s_waitcnt lgkmcnt(7)
	v_mfma_f32_16x16x32_bf16 v[124:127], v[160:163], v[0:3], v[228:231]
	s_waitcnt lgkmcnt(6)
	v_mfma_f32_16x16x32_bf16 v[128:131], v[168:171], v[0:3], v[228:231]
	s_waitcnt lgkmcnt(5)
	v_mfma_f32_16x16x32_bf16 v[132:135], v[176:179], v[0:3], v[228:231]
	s_waitcnt lgkmcnt(4)
	v_mfma_f32_16x16x32_bf16 v[136:139], v[184:187], v[0:3], v[228:231]
	s_waitcnt lgkmcnt(3)
	v_mfma_f32_16x16x32_bf16 v[124:127], v[164:167], v[4:7], v[124:127]
	s_waitcnt lgkmcnt(2)
	v_mfma_f32_16x16x32_bf16 v[128:131], v[172:175], v[4:7], v[128:131]
	s_waitcnt lgkmcnt(1)
	v_mfma_f32_16x16x32_bf16 v[132:135], v[180:183], v[4:7], v[132:135]
	s_waitcnt lgkmcnt(0)
	v_mfma_f32_16x16x32_bf16 v[136:139], v[188:191], v[4:7], v[136:139]
	s_waitcnt vmcnt(4)
	ds_write_b128 v244, v[104:107]
	ds_write_b128 v245, v[108:111]
	s_mov_b32 s16, s42
	s_ff1_i32_b32 s42, s38
	s_add_i32 s65, s38, -1
	s_and_b32 s38, s38, s65
	s_max_i32 s65, s42, 0
	s_mul_i32 s56, s65, 0x18000
	s_lshl_b32 s58, s65, 7
	s_add_u32 s56, s46, s56
	s_addc_u32 s57, s47, 0
	s_add_u32 s58, s48, s58
	s_addc_u32 s59, s49, 0
	global_load_dwordx4 v[104:107], v117, s[56:57]
	global_load_dwordx4 v[108:111], v118, s[58:59]
	s_cmp_eq_u32 s64, 0
	s_cbranch_scc1 .Lnsa_nm_13
	v_cndmask_b32_e64 v240, -1, v120, s[60:61]
	v_subrev_u32_e32 v220, 0, v240
	v_subrev_u32_e32 v221, 1, v240
	v_subrev_u32_e32 v222, 2, v240
	v_subrev_u32_e32 v223, 3, v240
	v_cmp_gt_u32_e64 s[52:53], s45, v220
	v_cmp_gt_u32_e64 s[54:55], s45, v221
	v_cmp_gt_u32_e64 s[56:57], s45, v222
	v_cmp_gt_u32_e64 s[58:59], s45, v223
	v_cndmask_b32_e64 v124, v224, v124, s[52:53]
	v_cndmask_b32_e64 v125, v224, v125, s[54:55]
	v_cndmask_b32_e64 v126, v224, v126, s[56:57]
	v_cndmask_b32_e64 v127, v224, v127, s[58:59]
	v_subrev_u32_e32 v220, 16, v240
	v_subrev_u32_e32 v221, 17, v240
	v_subrev_u32_e32 v222, 18, v240
	v_subrev_u32_e32 v223, 19, v240
	v_cmp_gt_u32_e64 s[52:53], s45, v220
	v_cmp_gt_u32_e64 s[54:55], s45, v221
	v_cmp_gt_u32_e64 s[56:57], s45, v222
	v_cmp_gt_u32_e64 s[58:59], s45, v223
	v_cndmask_b32_e64 v128, v224, v128, s[52:53]
	v_cndmask_b32_e64 v129, v224, v129, s[54:55]
	v_cndmask_b32_e64 v130, v224, v130, s[56:57]
	v_cndmask_b32_e64 v131, v224, v131, s[58:59]
	v_subrev_u32_e32 v220, 32, v240
	v_subrev_u32_e32 v221, 33, v240
	v_subrev_u32_e32 v222, 34, v240
	v_subrev_u32_e32 v223, 35, v240
	v_cmp_gt_u32_e64 s[52:53], s45, v220
	v_cmp_gt_u32_e64 s[54:55], s45, v221
	v_cmp_gt_u32_e64 s[56:57], s45, v222
	v_cmp_gt_u32_e64 s[58:59], s45, v223
	v_cndmask_b32_e64 v132, v224, v132, s[52:53]
	v_cndmask_b32_e64 v133, v224, v133, s[54:55]
	v_cndmask_b32_e64 v134, v224, v134, s[56:57]
	v_cndmask_b32_e64 v135, v224, v135, s[58:59]
	v_subrev_u32_e32 v220, 48, v240
	v_subrev_u32_e32 v221, 49, v240
	v_subrev_u32_e32 v222, 50, v240
	v_subrev_u32_e32 v223, 51, v240
	v_cmp_gt_u32_e64 s[52:53], s45, v220
	v_cmp_gt_u32_e64 s[54:55], s45, v221
	v_cmp_gt_u32_e64 s[56:57], s45, v222
	v_cmp_gt_u32_e64 s[58:59], s45, v223
	v_cndmask_b32_e64 v136, v224, v136, s[52:53]
	v_cndmask_b32_e64 v137, v224, v137, s[54:55]
	v_cndmask_b32_e64 v138, v224, v138, s[56:57]
	v_cndmask_b32_e64 v139, v224, v139, s[58:59]

.Lnsa_rb_17:
	s_waitcnt lgkmcnt(0)
	s_barrier
	s_mov_b32 s50, s17
	s_mov_b32 s15, s16
	v_mfma_f32_16x16x32_bf16 v[48:51], v[160:163], v[204:207], v[48:51]
	v_exp_f32_e32 v140, v140
	v_exp_f32_e32 v141, v141
	v_exp_f32_e32 v142, v142
	v_exp_f32_e32 v143, v143
	v_mfma_f32_16x16x32_bf16 v[52:55], v[168:171], v[204:207], v[52:55]
	v_exp_f32_e32 v144, v144
	v_exp_f32_e32 v145, v145
	v_exp_f32_e32 v146, v146
	v_exp_f32_e32 v147, v147
	v_mfma_f32_16x16x32_bf16 v[56:59], v[176:179], v[204:207], v[56:59]
	v_exp_f32_e32 v148, v148
	v_exp_f32_e32 v149, v149
	v_exp_f32_e32 v150, v150
	v_exp_f32_e32 v151, v151
	v_mfma_f32_16x16x32_bf16 v[60:63], v[184:187], v[204:207], v[60:63]
	v_exp_f32_e32 v154, v154
	v_exp_f32_e32 v155, v155
	v_exp_f32_e32 v156, v156
	v_exp_f32_e32 v157, v157
	v_mfma_f32_16x16x32_bf16 v[48:51], v[164:167], v[208:211], v[48:51]
	v_add_f32_e32 v232, v140, v141
	v_add_f32_e32 v232, v232, v142
	v_add_f32_e32 v232, v232, v143
	v_add_f32_e32 v232, v232, v144
	v_mfma_f32_16x16x32_bf16 v[52:55], v[172:175], v[208:211], v[52:55]
	v_add_f32_e32 v232, v232, v145
	v_add_f32_e32 v232, v232, v146
	v_add_f32_e32 v232, v232, v147
	v_add_f32_e32 v232, v232, v148
	v_mfma_f32_16x16x32_bf16 v[56:59], v[180:183], v[208:211], v[56:59]
	v_add_f32_e32 v232, v232, v149
	v_add_f32_e32 v232, v232, v150
	v_add_f32_e32 v232, v232, v151
	v_add_f32_e32 v232, v232, v154
	v_mfma_f32_16x16x32_bf16 v[60:63], v[188:191], v[208:211], v[60:63]
	v_add_f32_e32 v232, v232, v155
	v_add_f32_e32 v232, v232, v156
	v_add_f32_e32 v232, v232, v157
	v_add_f32_e32 v83, v83, v232
	v_cvt_pk_bf16_f32 v212, v140, v141
	v_cvt_pk_bf16_f32 v213, v142, v143
	v_cvt_pk_bf16_f32 v214, v144, v145
	v_cvt_pk_bf16_f32 v215, v146, v147
	v_cvt_pk_bf16_f32 v216, v148, v149
	v_cvt_pk_bf16_f32 v217, v150, v151
	v_cvt_pk_bf16_f32 v218, v154, v155
	v_cvt_pk_bf16_f32 v219, v156, v157
	v_mfma_f32_16x16x32_bf16 v[64:67], v[160:163], v[212:215], v[64:67]
	v_mfma_f32_16x16x32_bf16 v[68:71], v[168:171], v[212:215], v[68:71]
	v_mfma_f32_16x16x32_bf16 v[72:75], v[176:179], v[212:215], v[72:75]
	v_mfma_f32_16x16x32_bf16 v[76:79], v[184:187], v[212:215], v[76:79]
	v_mfma_f32_16x16x32_bf16 v[64:67], v[164:167], v[216:219], v[64:67]
	v_mfma_f32_16x16x32_bf16 v[68:71], v[172:175], v[216:219], v[68:71]
	v_mfma_f32_16x16x32_bf16 v[72:75], v[180:183], v[216:219], v[72:75]
	v_mfma_f32_16x16x32_bf16 v[76:79], v[188:191], v[216:219], v[76:79]
	s_cmp_lt_i32 s15, 0
	s_cbranch_scc1 .Lnsa_brk_6
	v_add_u32_e32 v225, s50, v115
	v_add_u32_e32 v246, s50, v122
	ds_read_b128 v[160:163], v225 offset:0
	ds_read_b128 v[168:171], v225 offset:2048
	ds_read_b128 v[176:179], v225 offset:4096
	ds_read_b128 v[184:187], v225 offset:6144
	ds_read_b128 v[164:167], v246 offset:0
	ds_read_b128 v[172:175], v246 offset:2048
	ds_read_b128 v[180:183], v246 offset:4096
	ds_read_b128 v[188:191], v246 offset:6144
	v_add_u32_e32 v247, s50, v116
	s_lshl_b32 s44, s15, 6
	s_lshl_b32 s65, 1, s15
	v_and_b32_e32 v220, s65, v248
	v_and_b32_e32 v221, s65, v249
	v_lshl_add_u32 v222, v113, 2, s44
	v_cmp_ne_u32_e64 s[60:61], 0, v220
	v_cmp_ne_u32_e64 s[62:63], 0, v221
	v_sub_u32_e32 v120, v86, v222
	v_sub_u32_e32 v121, v87, v222
	s_cmp_eq_u32 s15, s32
	s_cselect_b32 s64, 1, 0
	s_cmp_eq_u32 s15, s14
	s_cselect_b32 s64, 1, s64
	s_xor_b32 s17, s50, 0x4800
	v_add_u32_e32 v244, s17, v114
	v_add_u32_e32 v245, s17, v123
	v_cndmask_b32_e64 v228, v227, v80, s[60:61]
	v_cndmask_b32_e64 v229, v227, v80, s[60:61]
	v_cndmask_b32_e64 v230, v227, v80, s[60:61]
	v_cndmask_b32_e64 v231, v227, v80, s[60:61]
	v_cndmask_b32_e64 v236, v227, v81, s[62:63]
	v_cndmask_b32_e64 v237, v227, v81, s[62:63]
	v_cndmask_b32_e64 v238, v227, v81, s[62:63]
	v_cndmask_b32_e64 v239, v227, v81, s[62:63]
	s_waitcnt lgkmcnt(7)
	v_mfma_f32_16x16x32_bf16 v[124:127], v[160:163], v[0:3], v[228:231]
	s_waitcnt lgkmcnt(6)
	v_mfma_f32_16x16x32_bf16 v[128:131], v[168:171], v[0:3], v[228:231]
	s_waitcnt lgkmcnt(5)
	v_mfma_f32_16x16x32_bf16 v[132:135], v[176:179], v[0:3], v[228:231]
	s_waitcnt lgkmcnt(4)
	v_mfma_f32_16x16x32_bf16 v[136:139], v[184:187], v[0:3], v[228:231]
	s_waitcnt lgkmcnt(3)
	v_mfma_f32_16x16x32_bf16 v[124:127], v[164:167], v[4:7], v[124:127]
	s_waitcnt lgkmcnt(2)
	v_mfma_f32_16x16x32_bf16 v[128:131], v[172:175], v[4:7], v[128:131]
	s_waitcnt lgkmcnt(1)
	v_mfma_f32_16x16x32_bf16 v[132:135], v[180:183], v[4:7], v[132:135]
	s_waitcnt lgkmcnt(0)
	v_mfma_f32_16x16x32_bf16 v[136:139], v[188:191], v[4:7], v[136:139]
	s_waitcnt vmcnt(4)
	ds_write_b128 v244, v[88:91]
	ds_write_b128 v245, v[92:95]
	s_mov_b32 s16, s40
	s_ff1_i32_b32 s40, s38
	s_add_i32 s65, s38, -1
	s_and_b32 s38, s38, s65
	s_max_i32 s65, s40, 0
	s_mul_i32 s56, s65, 0x18000
	s_lshl_b32 s58, s65, 7
	s_add_u32 s56, s46, s56
	s_addc_u32 s57, s47, 0
	s_add_u32 s58, s48, s58
	s_addc_u32 s59, s49, 0
	global_load_dwordx4 v[88:91], v117, s[56:57]
	global_load_dwordx4 v[92:95], v118, s[58:59]
	s_cmp_eq_u32 s64, 0
	s_cbranch_scc1 .Lnsa_nm_19
	v_cndmask_b32_e64 v240, -1, v120, s[60:61]
	v_subrev_u32_e32 v220, 0, v240
	v_subrev_u32_e32 v221, 1, v240
	v_subrev_u32_e32 v222, 2, v240
	v_subrev_u32_e32 v223, 3, v240
	v_cmp_gt_u32_e64 s[52:53], s45, v220
	v_cmp_gt_u32_e64 s[54:55], s45, v221
	v_cmp_gt_u32_e64 s[56:57], s45, v222
	v_cmp_gt_u32_e64 s[58:59], s45, v223
	v_cndmask_b32_e64 v124, v224, v124, s[52:53]
	v_cndmask_b32_e64 v125, v224, v125, s[54:55]
	v_cndmask_b32_e64 v126, v224, v126, s[56:57]
	v_cndmask_b32_e64 v127, v224, v127, s[58:59]
	v_subrev_u32_e32 v220, 16, v240
	v_subrev_u32_e32 v221, 17, v240
	v_subrev_u32_e32 v222, 18, v240
	v_subrev_u32_e32 v223, 19, v240
	v_cmp_gt_u32_e64 s[52:53], s45, v220
	v_cmp_gt_u32_e64 s[54:55], s45, v221
	v_cmp_gt_u32_e64 s[56:57], s45, v222
	v_cmp_gt_u32_e64 s[58:59], s45, v223
	v_cndmask_b32_e64 v128, v224, v128, s[52:53]
	v_cndmask_b32_e64 v129, v224, v129, s[54:55]
	v_cndmask_b32_e64 v130, v224, v130, s[56:57]
	v_cndmask_b32_e64 v131, v224, v131, s[58:59]
	v_subrev_u32_e32 v220, 32, v240
	v_subrev_u32_e32 v221, 33, v240
	v_subrev_u32_e32 v222, 34, v240
	v_subrev_u32_e32 v223, 35, v240
	v_cmp_gt_u32_e64 s[52:53], s45, v220
	v_cmp_gt_u32_e64 s[54:55], s45, v221
	v_cmp_gt_u32_e64 s[56:57], s45, v222
	v_cmp_gt_u32_e64 s[58:59], s45, v223
	v_cndmask_b32_e64 v132, v224, v132, s[52:53]
	v_cndmask_b32_e64 v133, v224, v133, s[54:55]
	v_cndmask_b32_e64 v134, v224, v134, s[56:57]
	v_cndmask_b32_e64 v135, v224, v135, s[58:59]
	v_subrev_u32_e32 v220, 48, v240
	v_subrev_u32_e32 v221, 49, v240
	v_subrev_u32_e32 v222, 50, v240
	v_subrev_u32_e32 v223, 51, v240
	v_cmp_gt_u32_e64 s[52:53], s45, v220
	v_cmp_gt_u32_e64 s[54:55], s45, v221
	v_cmp_gt_u32_e64 s[56:57], s45, v222
	v_cmp_gt_u32_e64 s[58:59], s45, v223
	v_cndmask_b32_e64 v136, v224, v136, s[52:53]
	v_cndmask_b32_e64 v137, v224, v137, s[54:55]
	v_cndmask_b32_e64 v138, v224, v138, s[56:57]
	v_cndmask_b32_e64 v139, v224, v139, s[58:59]

.Lnsa_rb_23:
	s_waitcnt lgkmcnt(0)
	s_barrier
	s_mov_b32 s50, s17
	s_mov_b32 s15, s16
	v_mfma_f32_16x16x32_bf16 v[48:51], v[160:163], v[204:207], v[48:51]
	v_exp_f32_e32 v140, v140
	v_exp_f32_e32 v141, v141
	v_exp_f32_e32 v142, v142
	v_exp_f32_e32 v143, v143
	v_mfma_f32_16x16x32_bf16 v[52:55], v[168:171], v[204:207], v[52:55]
	v_exp_f32_e32 v144, v144
	v_exp_f32_e32 v145, v145
	v_exp_f32_e32 v146, v146
	v_exp_f32_e32 v147, v147
	v_mfma_f32_16x16x32_bf16 v[56:59], v[176:179], v[204:207], v[56:59]
	v_exp_f32_e32 v148, v148
	v_exp_f32_e32 v149, v149
	v_exp_f32_e32 v150, v150
	v_exp_f32_e32 v151, v151
	v_mfma_f32_16x16x32_bf16 v[60:63], v[184:187], v[204:207], v[60:63]
	v_exp_f32_e32 v154, v154
	v_exp_f32_e32 v155, v155
	v_exp_f32_e32 v156, v156
	v_exp_f32_e32 v157, v157
	v_mfma_f32_16x16x32_bf16 v[48:51], v[164:167], v[208:211], v[48:51]
	v_add_f32_e32 v232, v140, v141
	v_add_f32_e32 v232, v232, v142
	v_add_f32_e32 v232, v232, v143
	v_add_f32_e32 v232, v232, v144
	v_mfma_f32_16x16x32_bf16 v[52:55], v[172:175], v[208:211], v[52:55]
	v_add_f32_e32 v232, v232, v145
	v_add_f32_e32 v232, v232, v146
	v_add_f32_e32 v232, v232, v147
	v_add_f32_e32 v232, v232, v148
	v_mfma_f32_16x16x32_bf16 v[56:59], v[180:183], v[208:211], v[56:59]
	v_add_f32_e32 v232, v232, v149
	v_add_f32_e32 v232, v232, v150
	v_add_f32_e32 v232, v232, v151
	v_add_f32_e32 v232, v232, v154
	v_mfma_f32_16x16x32_bf16 v[60:63], v[188:191], v[208:211], v[60:63]
	v_add_f32_e32 v232, v232, v155
	v_add_f32_e32 v232, v232, v156
	v_add_f32_e32 v232, v232, v157
	v_add_f32_e32 v83, v83, v232
	v_cvt_pk_bf16_f32 v212, v140, v141
	v_cvt_pk_bf16_f32 v213, v142, v143
	v_cvt_pk_bf16_f32 v214, v144, v145
	v_cvt_pk_bf16_f32 v215, v146, v147
	v_cvt_pk_bf16_f32 v216, v148, v149
	v_cvt_pk_bf16_f32 v217, v150, v151
	v_cvt_pk_bf16_f32 v218, v154, v155
	v_cvt_pk_bf16_f32 v219, v156, v157
	v_mfma_f32_16x16x32_bf16 v[64:67], v[160:163], v[212:215], v[64:67]
	v_mfma_f32_16x16x32_bf16 v[68:71], v[168:171], v[212:215], v[68:71]
	v_mfma_f32_16x16x32_bf16 v[72:75], v[176:179], v[212:215], v[72:75]
	v_mfma_f32_16x16x32_bf16 v[76:79], v[184:187], v[212:215], v[76:79]
	v_mfma_f32_16x16x32_bf16 v[64:67], v[164:167], v[216:219], v[64:67]
	v_mfma_f32_16x16x32_bf16 v[68:71], v[172:175], v[216:219], v[68:71]
	v_mfma_f32_16x16x32_bf16 v[72:75], v[180:183], v[216:219], v[72:75]
	v_mfma_f32_16x16x32_bf16 v[76:79], v[188:191], v[216:219], v[76:79]
	s_branch .Lnsa_loop_5
.Lnsa_rr_8:
	v_mov_b32_e32 v221, v220
	s_nop 1
	v_permlane16_swap_b32_e32 v220, v221
	v_max_f32_e32 v220, v220, v221
	v_mov_b32_e32 v221, v220
	s_nop 1
	v_permlane32_swap_b32_e32 v220, v221
	v_max_f32_e32 v220, v220, v221
	v_cmp_gt_f32_e32 vcc, v220, v200
	s_nop 1
	v_cndmask_b32_e32 v221, 0, v220, vcc
	v_cndmask_b32_e32 v200, v200, v203, vcc
	v_max_f32_e32 v222, 0, v221
	v_exp_f32_e64 v222, -v222
	v_sub_f32_e32 v80, v80, v221
	v_sub_f32_e32 v124, v124, v221
	v_sub_f32_e32 v125, v125, v221
	v_sub_f32_e32 v126, v126, v221
	v_sub_f32_e32 v127, v127, v221
	v_sub_f32_e32 v128, v128, v221
	v_sub_f32_e32 v129, v129, v221
	v_sub_f32_e32 v130, v130, v221
	v_sub_f32_e32 v131, v131, v221
	v_sub_f32_e32 v132, v132, v221
	v_sub_f32_e32 v133, v133, v221
	v_sub_f32_e32 v134, v134, v221
	v_sub_f32_e32 v135, v135, v221
	v_sub_f32_e32 v136, v136, v221
	v_sub_f32_e32 v137, v137, v221
	v_sub_f32_e32 v138, v138, v221
	v_sub_f32_e32 v139, v139, v221
	v_mul_f32_e32 v82, v82, v222
	v_pk_mul_f32 v[48:49], v[48:49], v[222:223] op_sel_hi:[1,0]
	v_pk_mul_f32 v[50:51], v[50:51], v[222:223] op_sel_hi:[1,0]
	v_pk_mul_f32 v[52:53], v[52:53], v[222:223] op_sel_hi:[1,0]
	v_pk_mul_f32 v[54:55], v[54:55], v[222:223] op_sel_hi:[1,0]
	v_pk_mul_f32 v[56:57], v[56:57], v[222:223] op_sel_hi:[1,0]
	v_pk_mul_f32 v[58:59], v[58:59], v[222:223] op_sel_hi:[1,0]
	v_pk_mul_f32 v[60:61], v[60:61], v[222:223] op_sel_hi:[1,0]
	v_pk_mul_f32 v[62:63], v[62:63], v[222:223] op_sel_hi:[1,0]
	s_branch .Lnsa_rb_9
.Lnsa_rr_10:
	v_mov_b32_e32 v221, v220
	s_nop 1
	v_permlane16_swap_b32_e32 v220, v221
	v_max_f32_e32 v220, v220, v221
	v_mov_b32_e32 v221, v220
	s_nop 1
	v_permlane32_swap_b32_e32 v220, v221
	v_max_f32_e32 v220, v220, v221
	v_cmp_gt_f32_e32 vcc, v220, v201
	s_nop 1
	v_cndmask_b32_e32 v221, 0, v220, vcc
	v_cndmask_b32_e32 v201, v201, v203, vcc
	v_max_f32_e32 v222, 0, v221
	v_exp_f32_e64 v222, -v222
	v_sub_f32_e32 v81, v81, v221
	v_sub_f32_e32 v140, v140, v221
	v_sub_f32_e32 v141, v141, v221
	v_sub_f32_e32 v142, v142, v221
	v_sub_f32_e32 v143, v143, v221
	v_sub_f32_e32 v144, v144, v221
	v_sub_f32_e32 v145, v145, v221
	v_sub_f32_e32 v146, v146, v221
	v_sub_f32_e32 v147, v147, v221
	v_sub_f32_e32 v148, v148, v221
	v_sub_f32_e32 v149, v149, v221
	v_sub_f32_e32 v150, v150, v221
	v_sub_f32_e32 v151, v151, v221
	v_sub_f32_e32 v154, v154, v221
	v_sub_f32_e32 v155, v155, v221
	v_sub_f32_e32 v156, v156, v221
	v_sub_f32_e32 v157, v157, v221
	v_mul_f32_e32 v83, v83, v222
	v_pk_mul_f32 v[64:65], v[64:65], v[222:223] op_sel_hi:[1,0]
	v_pk_mul_f32 v[66:67], v[66:67], v[222:223] op_sel_hi:[1,0]
	v_pk_mul_f32 v[68:69], v[68:69], v[222:223] op_sel_hi:[1,0]
	v_pk_mul_f32 v[70:71], v[70:71], v[222:223] op_sel_hi:[1,0]
	v_pk_mul_f32 v[72:73], v[72:73], v[222:223] op_sel_hi:[1,0]
	v_pk_mul_f32 v[74:75], v[74:75], v[222:223] op_sel_hi:[1,0]
	v_pk_mul_f32 v[76:77], v[76:77], v[222:223] op_sel_hi:[1,0]
	v_pk_mul_f32 v[78:79], v[78:79], v[222:223] op_sel_hi:[1,0]
	s_branch .Lnsa_rb_11
